# ret_out item loop: the loop-top full vmcnt drain becomes vmcnt(4) (the previous item's four output stores stay in flight); first-item path drains before entering the loop
# baseline (speedup 1.0000x reference)
.Lp6_retout_entry:
	s_add_u32 s0, s22, 0x74bc000
	s_addc_u32 s1, s23, 0
	s_add_u32 s11, s22, 0x154bc000
	s_addc_u32 s13, s23, 0
	s_add_i32 s10, 0, 0x1b000
	s_ashr_i32 s6, s20, 7
	s_waitcnt vmcnt(0)
	v_lshrrev_b32_e32 v42, 6, v160
	s_movk_i32 s4, 0x1400
	v_mov_b32_e32 v0, s10
	s_and_b32 s16, s20, 31
	s_ashr_i32 s7, s6, 31
	v_mad_u32_u24 v73, v42, s4, v0
	s_lshl_b64 s[8:9], s[6:7], 12
	s_lshl_b32 s4, s16, 7
	s_or_b32 s8, s8, s4
	s_mul_i32 s4, s9, 0x1c00
	s_mul_hi_u32 s7, s8, 0x1c00
	s_bfe_u32 s12, s20, 0x20005
	s_add_i32 s7, s7, s4
	s_mul_i32 s4, s8, 0x1c00
	s_add_u32 s14, s0, s4
	s_addc_u32 s7, s1, s7
	s_lshl_b32 s4, s12, 8
	s_add_u32 s14, s14, s4
	s_addc_u32 s15, s7, 0
	s_lshl_b32 s6, s6, 2
	s_ashr_i32 s7, s6, 31
	s_or_b32 s6, s6, s12
	v_and_b32_e32 v162, 15, v160
	v_lshrrev_b32_e32 v164, 4, v160
	s_lshl_b64 s[6:7], s[6:7], 20
	s_add_u32 s6, s11, s6
	v_mov_b32_e32 v167, 0
	v_lshlrev_b32_e32 v166, 4, v162
	v_mul_u32_u24_e32 v68, 0xe00, v164
	s_addc_u32 s7, s13, s7
	s_lshl_b32 s12, s16, 15
	v_lshl_add_u64 v[0:1], s[14:15], 0, v[166:167]
	v_lshlrev_b32_e32 v2, 1, v68
	v_mov_b32_e32 v3, v167
	s_add_u32 s6, s6, s12
	v_lshl_add_u64 v[32:33], v[0:1], 0, v[2:3]
	s_mov_b32 s27, 0x38000
	s_addc_u32 s7, s7, 0
	v_lshlrev_b32_e32 v168, 4, v160
	v_mov_b32_e32 v169, v167
	v_add_co_u32_e32 v12, vcc, s27, v32
	v_lshl_add_u64 v[40:41], s[6:7], 0, v[168:169]
	s_nop 0
	v_addc_co_u32_e32 v13, vcc, 0, v33, vcc
	s_movk_i32 s28, 0x2000
	v_add_co_u32_e32 v16, vcc, s28, v40
	s_mov_b32 s29, 0x70000
	s_nop 0
	v_addc_co_u32_e32 v17, vcc, 0, v41, vcc
	v_add_co_u32_e32 v24, vcc, s29, v32
	s_movk_i32 s30, 0x4000
	s_nop 0
	v_addc_co_u32_e32 v25, vcc, 0, v33, vcc
	v_lshlrev_b32_e32 v70, 4, v42
	v_mov_b32_e32 v71, v167
	v_add_co_u32_e32 v28, vcc, s30, v40
	v_lshl_add_u64 v[42:43], s[8:9], 0, v[70:71]
	s_movk_i32 s26, 0x1c00
	v_addc_co_u32_e32 v29, vcc, 0, v41, vcc
	s_mov_b32 s12, 0xa8000
	v_or_b32_e32 v42, v42, v162
	v_mov_b64_e32 v[44:45], s[0:1]
	v_add_co_u32_e32 v36, vcc, s12, v32
	v_mad_u64_u32 v[44:45], s[8:9], v42, s26, v[44:45]
	s_mov_b32 s5, 0
	v_addc_co_u32_e32 v37, vcc, 0, v33, vcc
	s_movk_i32 s31, 0x6000
	v_mad_i32_i24 v45, v43, s26, v45
	v_add_co_u32_e32 v40, vcc, s31, v40
	v_lshl_add_u64 v[42:43], v[44:45], 0, s[4:5]
	v_and_b32_e32 v74, 48, v160
	v_mov_b32_e32 v75, v167
	v_addc_co_u32_e32 v41, vcc, 0, v41, vcc
	v_lshl_add_u64 v[60:61], v[42:43], 0, v[74:75]
	global_load_dwordx4 v[0:3], v[32:33], off offset:1024
	global_load_dwordx4 v[4:7], v[32:33], off offset:2048
	global_load_dwordx4 v[8:11], v[12:13], off offset:1024
	s_nop 0
	global_load_dwordx4 v[12:15], v[12:13], off offset:2048
	s_nop 0
	global_load_dwordx4 v[16:19], v[16:17], off
	s_nop 0
	global_load_dwordx4 v[20:23], v[24:25], off offset:1024
	s_nop 0
	global_load_dwordx4 v[24:27], v[24:25], off offset:2048
	s_nop 0
	global_load_dwordx4 v[28:31], v[28:29], off
	s_nop 0
	global_load_dwordx4 v[32:35], v[36:37], off offset:1024
	s_nop 0
	global_load_dwordx4 v[36:39], v[36:37], off offset:2048
	s_nop 0
	global_load_dwordx4 v[40:43], v[40:41], off
	s_nop 0
	global_load_dwordx4 v[44:47], v[60:61], off
	global_load_dwordx4 v[48:51], v[60:61], off offset:64
	global_load_dwordx4 v[52:55], v[60:61], off offset:128
	global_load_dwordx4 v[56:59], v168, s[6:7]
	s_nop 0
	global_load_dwordx4 v[60:63], v[60:61], off offset:192
	v_bfe_u32 v69, v160, 4, 2
	v_lshlrev_b32_e32 v66, 3, v160
	v_bfe_u32 v65, v160, 2, 2
	v_lshlrev_b32_e32 v72, 3, v69
	v_and_b32_e32 v71, 24, v66
	v_and_b32_e32 v67, 63, v160
	v_lshlrev_b32_e32 v64, 3, v162
	v_lshl_or_b32 v185, v69, 2, v70
	v_add_u32_e32 v77, v73, v72
	v_or_b32_e32 v65, v72, v65
	v_add_u32_e32 v73, v73, v71
	v_add_u32_e32 v79, 0, v71
	v_add_u32_e32 v80, s10, v166
	v_or_b32_e32 v170, v70, v162
	v_lshl_add_u64 v[70:71], s[22:23], 0, v[166:167]
	s_mov_b64 s[6:7], 0x30bc000
	s_movk_i32 s4, 0x130
	v_add_u32_e32 v174, 32, v164
	v_mov_b32_e32 v83, 0x2600
	v_add_u32_e32 v76, 0x200, v160
	v_or_b32_e32 v78, 0x400, v160
	v_add_u32_e32 v89, 0x600, v160
	v_add_u32_e32 v75, 0, v166
	v_add_u32_e32 v69, 0, v74
	v_mad_i32_i24 v81, v162, -14, v80
	v_lshl_add_u64 v[172:173], v[70:71], 0, s[6:7]
	v_mul_u32_u24_e32 v71, 0x110, v164
	v_mul_u32_u24_e32 v82, 0x130, v164
	v_mad_u32_u24 v84, v164, s4, v83
	v_mul_u32_u24_e32 v70, 0xe00, v174
	v_mul_u32_u24_e32 v85, 0x130, v162
	v_or_b32_e32 v180, 16, v162
	v_or_b32_e32 v182, 32, v162
	v_or_b32_e32 v184, 48, v162
	v_or_b32_e32 v186, 64, v162
	v_or_b32_e32 v188, 0x50, v162
	v_or_b32_e32 v190, 0x60, v162
	v_or_b32_e32 v192, 0x70, v162
	v_mul_u32_u24_e32 v86, 40, v162
	v_lshlrev_b32_e32 v74, 3, v76
	v_lshlrev_b32_e32 v87, 4, v76
	v_lshlrev_b32_e32 v76, 3, v78
	v_lshlrev_b32_e32 v88, 4, v78
	v_lshlrev_b32_e32 v78, 3, v89
	v_lshlrev_b32_e32 v89, 4, v89
	v_mul_u32_u24_e32 v90, 40, v65
	v_mul_u32_u24_e32 v91, 0x130, v65
	v_mad_u32_u24 v65, v65, s4, v83
	v_lshlrev_b32_e32 v187, 4, v67
	v_mul_u32_u24_e32 v67, 0x110, v174
	v_mul_u32_u24_e32 v83, 0x110, v185
	v_lshlrev_b32_e32 v166, 1, v64
	v_mbcnt_lo_u32_b32 v64, -1, 0
	v_mov_b32_e32 v171, v167
	v_or_b32_e32 v176, 64, v164
	v_add_u32_e32 v178, 0x60, v164
	v_mov_b32_e32 v179, v167
	v_mov_b32_e32 v161, v162
	v_mov_b32_e32 v163, v180
	v_mov_b32_e32 v165, v182
	v_mov_b32_e32 v169, v184
	v_mov_b32_e32 v175, v186
	v_mov_b32_e32 v177, v188
	v_mov_b32_e32 v181, v190
	v_mov_b32_e32 v183, v192
	s_mov_b32 s38, 0x3f2aaaab
	v_mov_b32_e32 v189, 0x3ecc95a3
	s_mov_b32 s39, 0x3f317218
	s_mov_b32 s40, 0xff800000
	s_mov_b32 s41, 0x33800000
	v_add_u32_e32 v191, v75, v82
	s_add_i32 s42, 0, 0x13000
	v_add_u32_e32 v193, v75, v84
	v_lshlrev_b32_e32 v194, 1, v68
	v_lshlrev_b32_e32 v196, 1, v70
	v_add_u32_e32 v204, v69, v85
	v_add_u32_e32 v205, v77, v86
	v_lshlrev_b32_e32 v198, 1, v66
	v_lshlrev_b32_e32 v206, 1, v74
	v_add_u32_e32 v207, 0, v87
	v_lshlrev_b32_e32 v208, 1, v76
	v_add_u32_e32 v209, 0, v88
	v_lshlrev_b32_e32 v210, 1, v78
	v_add_u32_e32 v211, 0, v89
	v_add_u32_e32 v212, v73, v90
	v_add_u32_e32 v213, v79, v91
	v_add_u32_e32 v214, v79, v65
	s_mov_b64 s[6:7], 0x38000
	s_mov_b64 s[8:9], 0x70000
	v_lshlrev_b32_e32 v200, 1, v72
	v_mbcnt_hi_u32_b32 v215, -1, v64
	v_add_u32_e32 v216, v81, v83
	s_brev_b32 s10, 60
	s_mov_b32 s12, 0x358637bd
	s_mov_b32 s43, 0x800000
	s_movk_i32 s44, 0x7fff
	v_mov_b32_e32 v202, 0x3f317218
	v_mov_b32_e32 v217, 0x7f800000
	v_mov_b32_e32 v218, 0x7fc00000
	v_mov_b32_e32 v219, 0xff800000
	v_add_u32_e32 v220, v80, v71
	v_add_u32_e32 v221, v80, v67
	s_mov_b32 s45, s20
	s_bfe_u32 s98, s45, 0x20005
	s_lshl_b32 s98, s98, 2
	v_mov_b32_e32 v241, s98
	global_load_dword v242, v241, s[54:55]
	global_load_dword v243, v241, s[54:55] offset:16
	s_waitcnt vmcnt(0)
	s_branch .LBB0_903

.LBB0_903:
	s_bfe_u32 s4, s45, 0x20005
	s_lshl_b32 s14, s4, 2
	v_mov_b32_e32 v64, s14
	s_nop 0
	s_ashr_i32 s16, s45, 7
	s_and_b32 s47, s45, 31
	s_ashr_i32 s17, s16, 31
	s_lshl_b32 s46, s47, 7
	v_mov_b32_e32 v197, v167
	v_mov_b32_e32 v195, v167
	v_mov_b32_e32 v229, v185
	s_waitcnt vmcnt(4)
	v_mul_f32_e32 v65, 0x3fb8aa3b, v242
	v_exp_f32_e32 v68, v65
	v_mul_f32_e32 v64, 0x3fb8aa3b, v243
	v_exp_f32_e32 v98, v64
	v_sub_f32_e32 v69, 1.0, v68
	v_frexp_mant_f32_e32 v72, v69
	v_cvt_f64_f32_e32 v[64:65], v69
	v_sub_f32_e32 v70, 1.0, v98
	v_add_f32_e32 v71, -1.0, v69
	v_frexp_exp_i32_f64_e32 v64, v[64:65]
	v_cmp_gt_f32_e32 vcc, s38, v72
	v_add_f32_e32 v73, -1.0, v70
	v_frexp_mant_f32_e32 v74, v70
	v_cvt_f64_f32_e32 v[66:67], v70
	v_sub_f32_e32 v75, v71, v69
	v_subbrev_co_u32_e32 v64, vcc, 0, v64, vcc
	v_sub_f32_e64 v71, -v68, v71
	v_sub_f32_e32 v65, v73, v70
	v_frexp_exp_i32_f64_e32 v66, v[66:67]
	v_add_f32_e32 v67, 1.0, v75
	v_cmp_gt_f32_e32 vcc, s38, v74
	v_sub_f32_e64 v73, -v98, v73
	v_add_f32_e32 v65, 1.0, v65
	v_subbrev_co_u32_e32 v82, vcc, 0, v66, vcc
	v_add_f32_e32 v66, v71, v67
	v_sub_u32_e32 v67, 0, v64
	v_add_f32_e32 v65, v73, v65
	v_sub_u32_e32 v71, 0, v82
	v_ldexp_f32 v69, v69, v67
	v_ldexp_f32 v66, v66, v67
	v_ldexp_f32 v67, v70, v71
	v_ldexp_f32 v65, v65, v71
	v_add_f32_e32 v70, -1.0, v69
	v_add_f32_e32 v71, 1.0, v69
	v_add_f32_e32 v74, 1.0, v70
	v_add_f32_e32 v75, -1.0, v71
	v_add_f32_e32 v72, -1.0, v67
	v_sub_f32_e32 v74, v69, v74
	v_sub_f32_e32 v69, v69, v75
	v_add_f32_e32 v73, 1.0, v67
	v_add_f32_e32 v76, 1.0, v72
	v_add_f32_e32 v74, v66, v74
	v_add_f32_e32 v66, v66, v69
	v_add_f32_e32 v77, -1.0, v73
	v_sub_f32_e32 v75, v67, v76
	v_add_f32_e32 v76, v71, v66
	v_sub_f32_e32 v67, v67, v77
	v_rcp_f32_e32 v77, v76
	v_add_f32_e32 v75, v65, v75
	v_add_f32_e32 v65, v65, v67
	v_add_f32_e32 v83, v73, v65
	v_add_f32_e32 v67, v70, v74
	v_sub_f32_e32 v73, v83, v73
	v_add_f32_e32 v69, v72, v75
	v_sub_f32_e32 v70, v67, v70
	v_sub_f32_e32 v85, v65, v73
	v_mul_f32_e32 v65, v67, v77
	v_sub_f32_e32 v71, v76, v71
	v_sub_f32_e32 v72, v69, v72
	v_sub_f32_e32 v74, v74, v70
	v_mul_f32_e32 v70, v76, v65
	v_sub_f32_e32 v78, v66, v71
	v_sub_f32_e32 v86, v75, v72
	v_fma_f32 v72, v65, v76, -v70
	v_fmac_f32_e32 v72, v65, v78
	v_add_f32_e32 v66, v70, v72
	v_sub_f32_e32 v71, v67, v66
	v_mov_b32_e32 v73, v66
	v_pk_add_f32 v[66:67], v[66:67], v[70:71] neg_lo:[0,1] neg_hi:[0,1]
	v_cvt_f32_i32_e32 v64, v64
	v_pk_add_f32 v[66:67], v[66:67], v[72:73] neg_lo:[0,1] neg_hi:[0,1]
	v_rcp_f32_e32 v84, v83
	v_add_f32_e32 v67, v74, v67
	v_add_f32_e32 v66, v66, v67
	v_add_f32_e32 v67, v71, v66
	v_mul_f32_e32 v73, v77, v67
	v_mul_f32_e32 v70, v76, v73
	v_fma_f32 v72, v73, v76, -v70
	v_sub_f32_e32 v71, v71, v67
	v_fmac_f32_e32 v72, v73, v78
	v_add_f32_e32 v74, v66, v71
	v_add_f32_e32 v75, v65, v73
	v_add_f32_e32 v66, v70, v72
	v_sub_f32_e32 v65, v75, v65
	v_sub_f32_e32 v71, v67, v66
	v_sub_f32_e32 v65, v73, v65
	v_mov_b32_e32 v73, v66
	v_pk_add_f32 v[66:67], v[66:67], v[70:71] neg_lo:[0,1] neg_hi:[0,1]
	v_cmp_neq_f32_e32 vcc, s40, v68
	v_pk_add_f32 v[66:67], v[66:67], v[72:73] neg_lo:[0,1] neg_hi:[0,1]
	v_mul_f32_e32 v87, v69, v84
	v_add_f32_e32 v67, v74, v67
	v_add_f32_e32 v66, v66, v67
	v_add_f32_e32 v66, v71, v66
	v_mul_f32_e32 v66, v77, v66
	v_add_f32_e32 v65, v65, v66
	v_add_f32_e32 v66, v75, v65
	v_mul_f32_e32 v70, v66, v66
	v_sub_f32_e32 v71, v66, v75
	v_fmamk_f32 v72, v70, 0x3e9b6dac, v189
	v_sub_f32_e32 v71, v65, v71
	v_mul_f32_e32 v65, v66, v70
	v_fmaak_f32 v203, v70, v72, 0x3f2aaada
	v_ldexp_f32 v73, v71, 1
	v_pk_mul_f32 v[70:71], v[64:65], v[202:203]
	v_ldexp_f32 v67, v66, 1
	v_fma_f32 v66, v64, s39, -v70
	v_fmac_f32_e32 v66, 0xb102e308, v64
	v_pk_add_f32 v[64:65], v[70:71], v[66:67]
	v_mov_b32_e32 v72, v70
	v_sub_f32_e32 v76, v65, v67
	v_pk_add_f32 v[74:75], v[64:65], v[70:71] neg_lo:[0,1] neg_hi:[0,1]
	v_sub_f32_e32 v71, v71, v76
	v_add_f32_e32 v73, v73, v71
	v_pk_add_f32 v[78:79], v[64:65], v[72:73]
	v_mov_b32_e32 v67, v64
	v_mov_b32_e32 v75, v79
	v_pk_add_f32 v[80:81], v[66:67], v[74:75] neg_lo:[0,1] neg_hi:[0,1]
	v_pk_add_f32 v[66:67], v[66:67], v[74:75]
	v_mov_b32_e32 v70, v65
	v_mov_b32_e32 v77, v64
	v_pk_add_f32 v[64:65], v[66:67], v[64:65] op_sel:[1,0] op_sel_hi:[0,1] neg_lo:[0,1] neg_hi:[0,1]
	v_mov_b32_e32 v76, v73
	v_mov_b32_e32 v72, v79
	v_mov_b32_e32 v73, v67
	v_mov_b32_e32 v71, v64
	v_pk_add_f32 v[74:75], v[78:79], v[64:65] op_sel_hi:[1,0] neg_lo:[0,1] neg_hi:[0,1]
	v_pk_add_f32 v[64:65], v[72:73], v[70:71] neg_lo:[0,1] neg_hi:[0,1]
	v_mov_b32_e32 v74, v80
	v_pk_add_f32 v[64:65], v[76:77], v[64:65] neg_lo:[0,1] neg_hi:[0,1]
	v_mov_b32_e32 v81, v67
	v_pk_add_f32 v[70:71], v[74:75], v[64:65]
	v_cmp_lt_f32_e64 s[14:15], |v68|, s41
	v_pk_add_f32 v[72:73], v[70:71], v[70:71] op_sel:[0,1] op_sel_hi:[1,0]
	s_nop 0
	v_pk_add_f32 v[66:67], v[66:67], v[72:73] op_sel:[1,0] op_sel_hi:[0,1]
	v_mov_b32_e32 v71, v66
	v_mov_b32_e32 v65, v72
	v_pk_add_f32 v[72:73], v[70:71], v[80:81] neg_lo:[0,1] neg_hi:[0,1]
	s_nop 0
	v_sub_f32_e32 v67, v70, v72
	v_pk_add_f32 v[64:65], v[64:65], v[72:73] neg_lo:[0,1] neg_hi:[0,1]
	v_sub_f32_e32 v67, v80, v67
	v_add_f32_e32 v64, v64, v67
	v_add_f32_e32 v64, v64, v65
	v_add_f32_e32 v64, v66, v64
	v_cndmask_b32_e32 v64, v217, v64, vcc
	v_cmp_nlt_f32_e32 vcc, 1.0, v68
	s_nop 1
	v_cndmask_b32_e32 v64, v218, v64, vcc
	v_cmp_neq_f32_e32 vcc, 1.0, v68
	s_nop 1
	v_cndmask_b32_e32 v64, v219, v64, vcc
	v_cndmask_b32_e64 v99, v64, -v68, s[14:15]
	v_mul_f32_e32 v64, v83, v87
	v_fma_f32 v66, v87, v83, -v64
	v_fmac_f32_e32 v66, v87, v85
	v_add_f32_e32 v68, v64, v66
	v_sub_f32_e32 v65, v69, v68
	v_pk_add_f32 v[70:71], v[68:69], v[64:65] neg_lo:[0,1] neg_hi:[0,1]
	v_mov_b32_e32 v67, v68
	v_pk_add_f32 v[66:67], v[70:71], v[66:67] neg_lo:[0,1] neg_hi:[0,1]
	s_lshl_b64 s[14:15], s[16:17], 12
	v_add_f32_e32 v64, v86, v67
	v_add_f32_e32 v66, v66, v64
	v_add_f32_e32 v67, v65, v66
	v_mul_f32_e32 v72, v84, v67
	v_mul_f32_e32 v64, v83, v72
	v_fma_f32 v68, v72, v83, -v64
	v_fmac_f32_e32 v68, v72, v85
	v_sub_f32_e32 v65, v65, v67
	v_add_f32_e32 v73, v66, v65
	v_add_f32_e32 v66, v64, v68
	v_sub_f32_e32 v65, v67, v66
	v_pk_add_f32 v[70:71], v[66:67], v[64:65] neg_lo:[0,1] neg_hi:[0,1]
	v_mov_b32_e32 v69, v66
	v_pk_add_f32 v[66:67], v[70:71], v[68:69] neg_lo:[0,1] neg_hi:[0,1]
	s_or_b32 s14, s14, s46
	v_add_f32_e32 v64, v73, v67
	v_add_f32_e32 v64, v66, v64
	v_add_f32_e32 v64, v65, v64
	v_add_f32_e32 v65, v87, v72
	v_sub_f32_e32 v66, v65, v87
	v_mul_f32_e32 v64, v84, v64
	v_sub_f32_e32 v66, v72, v66
	v_add_f32_e32 v66, v66, v64
	v_add_f32_e32 v67, v65, v66
	v_mul_f32_e32 v68, v67, v67
	v_fmamk_f32 v64, v68, 0x3e9b6dac, v189
	v_fmaak_f32 v203, v68, v64, 0x3f2aaada
	v_cvt_f32_i32_e32 v64, v82
	v_sub_f32_e32 v65, v67, v65
	v_sub_f32_e32 v65, v66, v65
	v_ldexp_f32 v86, v65, 1
	v_mul_f32_e32 v65, v67, v68
	s_mul_i32 s17, s15, 0x1c00
	s_mul_hi_u32 s46, s14, 0x1c00
	v_pk_mul_f32 v[82:83], v[64:65], v[202:203]
	s_add_i32 s46, s46, s17
	s_mul_i32 s17, s14, 0x1c00
	v_fma_f32 v80, v64, s39, -v82
	s_add_u32 s17, s0, s17
	v_ldexp_f32 v81, v67, 1
	v_fmac_f32_e32 v80, 0xb102e308, v64
	s_addc_u32 s49, s1, s46
	s_lshl_b32 s46, s4, 7
	s_lshl_b32 s48, s4, 8
	v_pk_add_f32 v[84:85], v[82:83], v[80:81]
	s_add_u32 s48, s17, s48
	v_sub_f32_e32 v64, v85, v81
	s_addc_u32 s49, s49, 0
	v_sub_f32_e32 v81, v83, v64
	v_lshl_add_u64 v[64:65], s[48:49], 0, v[166:167]
	v_lshl_add_u64 v[72:73], v[64:65], 0, v[196:197]
	v_add_co_u32_e32 v74, vcc, s27, v72
	v_or_b32_e32 v87, s46, v162
	s_nop 0
	v_addc_co_u32_e32 v75, vcc, 0, v73, vcc
	v_add_co_u32_e32 v76, vcc, s29, v72
	v_lshl_add_u64 v[66:67], v[64:65], 0, v[194:195]
	s_nop 0
	v_addc_co_u32_e32 v77, vcc, 0, v73, vcc
	v_lshlrev_b32_e32 v87, 2, v87
	global_load_dwordx4 v[64:67], v[66:67], off offset:3072
	s_nop 0
	global_load_dwordx4 v[68:71], v[72:73], off offset:3072
	s_nop 0
	global_load_dwordx4 v[72:75], v[74:75], off offset:3072
	s_nop 0
	global_load_dwordx4 v[76:79], v[76:77], off offset:3072
	s_nop 0
	global_load_dword v228, v87, s[56:57]
	global_load_dword v227, v87, s[56:57] offset:64
	global_load_dword v226, v87, s[56:57] offset:128
	global_load_dword v225, v87, s[56:57] offset:192
	global_load_dword v224, v87, s[56:57] offset:256
	global_load_dword v223, v87, s[56:57] offset:320
	global_load_dword v222, v87, s[56:57] offset:384
	global_load_dword v203, v87, s[56:57] offset:448
	v_add_f32_e32 v87, v86, v81
	v_mov_b32_e32 v86, v82
	v_pk_add_f32 v[82:83], v[84:85], v[82:83] neg_lo:[0,1] neg_hi:[0,1]
	v_pk_add_f32 v[88:89], v[84:85], v[86:87]
	v_mov_b32_e32 v81, v84
	v_mov_b32_e32 v83, v89
	v_pk_add_f32 v[92:93], v[80:81], v[82:83] neg_lo:[0,1] neg_hi:[0,1]
	v_pk_add_f32 v[80:81], v[80:81], v[82:83]
	v_mov_b32_e32 v94, v85
	v_pk_add_f32 v[82:83], v[80:81], v[84:85] op_sel:[1,0] op_sel_hi:[0,1] neg_lo:[0,1] neg_hi:[0,1]
	v_pk_add_f32 v[90:91], v[88:89], v[82:83] op_sel_hi:[1,0] neg_lo:[0,1] neg_hi:[0,1]
	v_mov_b32_e32 v88, v89
	v_mov_b32_e32 v89, v81
	v_mov_b32_e32 v95, v82
	v_pk_add_f32 v[82:83], v[88:89], v[94:95] neg_lo:[0,1] neg_hi:[0,1]
	v_mov_b32_e32 v86, v87
	v_mov_b32_e32 v87, v84
	v_pk_add_f32 v[84:85], v[86:87], v[82:83] neg_lo:[0,1] neg_hi:[0,1]
	v_mov_b32_e32 v90, v92
	v_pk_add_f32 v[88:89], v[90:91], v[84:85]
	ds_write_b128 v191, v[0:3]
	ds_write_b128 v191, v[4:7] offset:38912
	v_pk_add_f32 v[86:87], v[88:89], v[88:89] op_sel:[0,1] op_sel_hi:[1,0]
	v_mov_b32_e32 v93, v81
	v_pk_add_f32 v[94:95], v[80:81], v[86:87] op_sel:[1,0] op_sel_hi:[0,1]
	v_add_u32_e32 v80, s42, v168
	ds_write_b128 v80, v[56:59]
	ds_write_b128 v191, v[8:11] offset:9728
	ds_write_b128 v191, v[12:15] offset:48640
	ds_write_b128 v80, v[16:19] offset:8192
	ds_write_b128 v191, v[20:23] offset:19456
	ds_write_b128 v191, v[24:27] offset:58368
	ds_write_b128 v80, v[28:31] offset:16384
	ds_write_b128 v191, v[32:35] offset:29184
	ds_write_b128 v193, v[36:39] offset:58368
	ds_write_b128 v80, v[40:43] offset:24576
	s_waitcnt lgkmcnt(0)
	s_barrier
	ds_read_b128 v[80:83], v204
	v_mov_b32_e32 v89, v94
	v_pk_add_f32 v[90:91], v[88:89], v[92:93] neg_lo:[0,1] neg_hi:[0,1]
	v_mov_b32_e32 v85, v86
	v_pk_add_f32 v[96:97], v[84:85], v[90:91] neg_lo:[0,1] neg_hi:[0,1]
	ds_read_b128 v[84:87], v204 offset:64
	s_waitcnt lgkmcnt(0)
	v_mfma_f32_16x16x32_bf16 v[80:83], v[44:47], v[80:83], 0
	v_sub_f32_e32 v93, v88, v90
	ds_read_b128 v[88:91], v204 offset:128
	v_cmp_neq_f32_e32 vcc, s40, v98
	v_mfma_f32_16x16x32_bf16 v[80:83], v[48:51], v[84:87], v[80:83]
	v_sub_f32_e32 v84, v92, v93
	v_add_f32_e32 v92, v96, v84
	ds_read_b128 v[84:87], v204 offset:192
	s_waitcnt lgkmcnt(1)
	v_mfma_f32_16x16x32_bf16 v[80:83], v[52:55], v[88:91], v[80:83]
	v_add_f32_e32 v88, v92, v97
	v_add_f32_e32 v92, v94, v88
	ds_read_b128 v[88:91], v204 offset:4864
	s_waitcnt lgkmcnt(1)
	v_mfma_f32_16x16x32_bf16 v[100:103], v[60:63], v[84:87], v[80:83]
	v_cndmask_b32_e32 v92, v217, v92, vcc
	v_cmp_nlt_f32_e32 vcc, 1.0, v98
	v_cmp_lt_f32_e64 s[48:49], |v98|, s41
	ds_read_b128 v[80:83], v204 offset:4928
	s_waitcnt lgkmcnt(1)
	v_mfma_f32_16x16x32_bf16 v[84:87], v[44:47], v[88:91], 0
	ds_read_b128 v[88:91], v204 offset:4992
	v_cndmask_b32_e32 v92, v218, v92, vcc
	v_cmp_neq_f32_e32 vcc, 1.0, v98
	s_waitcnt lgkmcnt(1)
	v_mfma_f32_16x16x32_bf16 v[80:83], v[48:51], v[80:83], v[84:87]
	v_mul_f32_e32 v230, 0x3fb8aa3b, v99
	v_cndmask_b32_e32 v92, v219, v92, vcc
	v_cndmask_b32_e64 v120, v92, -v98, s[48:49]
	ds_read_b128 v[84:87], v204 offset:5056
	s_waitcnt lgkmcnt(1)
	v_mfma_f32_16x16x32_bf16 v[80:83], v[52:55], v[88:91], v[80:83]
	s_lshl_b32 s16, s16, 2
	s_waitcnt lgkmcnt(0)
	v_mfma_f32_16x16x32_bf16 v[104:107], v[60:63], v[84:87], v[80:83]
	s_nop 4
	ds_read_b128 v[80:83], v204 offset:9728
	ds_read_b128 v[84:87], v204 offset:9792
	s_waitcnt lgkmcnt(1)
	v_mfma_f32_16x16x32_bf16 v[80:83], v[44:47], v[80:83], 0
	s_waitcnt lgkmcnt(0)
	v_mfma_f32_16x16x32_bf16 v[80:83], v[48:51], v[84:87], v[80:83]
	ds_read_b128 v[84:87], v204 offset:9856
	ds_read_b128 v[88:91], v204 offset:9920
	s_waitcnt lgkmcnt(1)
	v_mfma_f32_16x16x32_bf16 v[80:83], v[52:55], v[84:87], v[80:83]
	s_waitcnt lgkmcnt(0)
	v_mfma_f32_16x16x32_bf16 v[108:111], v[60:63], v[88:91], v[80:83]
	s_nop 5
	ds_read_b128 v[80:83], v204 offset:14592
	ds_read_b128 v[84:87], v204 offset:14656
	s_waitcnt lgkmcnt(1)
	v_mfma_f32_16x16x32_bf16 v[80:83], v[44:47], v[80:83], 0
	s_waitcnt lgkmcnt(0)
	v_mfma_f32_16x16x32_bf16 v[80:83], v[48:51], v[84:87], v[80:83]
	ds_read_b128 v[84:87], v204 offset:14720
	ds_read_b128 v[88:91], v204 offset:14784
	s_waitcnt lgkmcnt(1)
	v_mfma_f32_16x16x32_bf16 v[80:83], v[52:55], v[84:87], v[80:83]
	s_waitcnt lgkmcnt(0)
	v_mfma_f32_16x16x32_bf16 v[96:99], v[60:63], v[88:91], v[80:83]
	s_nop 5
	ds_read_b128 v[80:83], v204 offset:19456
	ds_read_b128 v[84:87], v204 offset:19520
	s_waitcnt lgkmcnt(1)
	v_mfma_f32_16x16x32_bf16 v[80:83], v[44:47], v[80:83], 0
	s_waitcnt lgkmcnt(0)
	v_mfma_f32_16x16x32_bf16 v[80:83], v[48:51], v[84:87], v[80:83]
	ds_read_b128 v[84:87], v204 offset:19584
	ds_read_b128 v[88:91], v204 offset:19648
	s_waitcnt lgkmcnt(1)
	v_mfma_f32_16x16x32_bf16 v[80:83], v[52:55], v[84:87], v[80:83]
	s_waitcnt lgkmcnt(0)
	v_mfma_f32_16x16x32_bf16 v[92:95], v[60:63], v[88:91], v[80:83]
	s_nop 5
	ds_read_b128 v[80:83], v204 offset:24320
	ds_read_b128 v[84:87], v204 offset:24384
	s_waitcnt lgkmcnt(1)
	v_mfma_f32_16x16x32_bf16 v[80:83], v[44:47], v[80:83], 0
	s_waitcnt lgkmcnt(0)
	v_mfma_f32_16x16x32_bf16 v[80:83], v[48:51], v[84:87], v[80:83]
	ds_read_b128 v[84:87], v204 offset:24448
	ds_read_b128 v[88:91], v204 offset:24512
	s_waitcnt lgkmcnt(1)
	v_mfma_f32_16x16x32_bf16 v[80:83], v[52:55], v[84:87], v[80:83]
	s_waitcnt lgkmcnt(0)
	v_mfma_f32_16x16x32_bf16 v[88:91], v[60:63], v[88:91], v[80:83]
	s_nop 5
	ds_read_b128 v[80:83], v204 offset:29184
	ds_read_b128 v[84:87], v204 offset:29248
	s_waitcnt lgkmcnt(1)
	v_mfma_f32_16x16x32_bf16 v[80:83], v[44:47], v[80:83], 0
	s_waitcnt lgkmcnt(0)
	v_mfma_f32_16x16x32_bf16 v[80:83], v[48:51], v[84:87], v[80:83]
	ds_read_b128 v[84:87], v204 offset:29312
	ds_read_b128 v[112:115], v204 offset:29376
	s_waitcnt lgkmcnt(1)
	v_mfma_f32_16x16x32_bf16 v[80:83], v[52:55], v[84:87], v[80:83]
	s_waitcnt lgkmcnt(0)
	v_mfma_f32_16x16x32_bf16 v[84:87], v[60:63], v[112:115], v[80:83]
	s_nop 5
	ds_read_b128 v[80:83], v204 offset:34048
	ds_read_b128 v[112:115], v204 offset:34112
	s_waitcnt lgkmcnt(1)
	v_mfma_f32_16x16x32_bf16 v[80:83], v[44:47], v[80:83], 0
	s_waitcnt lgkmcnt(0)
	v_mfma_f32_16x16x32_bf16 v[80:83], v[48:51], v[112:115], v[80:83]
	ds_read_b128 v[112:115], v204 offset:34176
	ds_read_b128 v[116:119], v204 offset:34240
	s_waitcnt lgkmcnt(1)
	v_mfma_f32_16x16x32_bf16 v[80:83], v[52:55], v[112:115], v[80:83]
	s_waitcnt lgkmcnt(0)
	v_mfma_f32_16x16x32_bf16 v[80:83], v[60:63], v[116:119], v[80:83]
	v_add_u32_e32 v232, 1, v229
	v_sub_u32_e32 v114, v232, v162
	v_sub_u32_e32 v112, v229, v162
	v_cvt_f32_i32_e32 v115, v114
	v_mul_f32_e32 v231, 0x3fb8aa3b, v120
	v_cmp_lt_i32_e32 vcc, 0, v112
	v_cvt_f32_i32_e32 v112, v112
	v_add_u32_e32 v233, 3, v229
	v_cndmask_b32_e64 v113, -v231, v230, vcc
	v_cmp_lt_i32_e32 vcc, 0, v114
	v_mul_f32_e32 v112, v113, v112
	v_exp_f32_e32 v112, v112
	v_cndmask_b32_e64 v114, -v231, v230, vcc
	v_mul_f32_e32 v114, v114, v115
	v_exp_f32_e32 v114, v114
	v_cmp_ne_u32_e32 vcc, v232, v161
	v_add_u32_e32 v234, 2, v229
	s_or_b32 s4, s16, s4
	v_cndmask_b32_e32 v113, 2.0, v114, vcc
	v_cmp_ne_u32_e32 vcc, v229, v162
	v_sub_u32_e32 v114, v233, v162
	v_cvt_f32_i32_e32 v115, v114
	v_cndmask_b32_e32 v112, 2.0, v112, vcc
	v_pk_mul_f32 v[100:101], v[100:101], v[112:113]
	v_sub_u32_e32 v112, v234, v162
	v_cmp_lt_i32_e32 vcc, 0, v112
	v_cvt_f32_i32_e32 v112, v112
	v_cvt_pk_bf16_f32 v100, v100, v101
	v_cndmask_b32_e64 v113, -v231, v230, vcc
	v_cmp_lt_i32_e32 vcc, 0, v114
	v_mul_f32_e32 v112, v113, v112
	v_exp_f32_e32 v112, v112
	v_cndmask_b32_e64 v114, -v231, v230, vcc
	v_mul_f32_e32 v114, v114, v115
	v_exp_f32_e32 v114, v114
	v_cmp_ne_u32_e32 vcc, v233, v161
	s_add_i32 s16, s4, 32
	s_ashr_i32 s17, s16, 31
	v_cndmask_b32_e32 v113, 2.0, v114, vcc
	v_cmp_ne_u32_e32 vcc, v234, v162
	s_lshl_b64 s[16:17], s[16:17], 20
	s_add_u32 s4, s11, s16
	v_cndmask_b32_e32 v112, 2.0, v112, vcc
	v_pk_mul_f32 v[102:103], v[102:103], v[112:113]
	v_sub_u32_e32 v112, v232, v180
	v_cvt_pk_bf16_f32 v101, v102, v103
	v_sub_u32_e32 v102, v229, v180
	v_cvt_f32_i32_e32 v113, v112
	v_cmp_lt_i32_e32 vcc, 0, v102
	v_cvt_f32_i32_e32 v102, v102
	s_addc_u32 s17, s13, s17
	v_cndmask_b32_e64 v103, -v231, v230, vcc
	v_cmp_lt_i32_e32 vcc, 0, v112
	v_mul_f32_e32 v102, v103, v102
	v_exp_f32_e32 v102, v102
	v_cndmask_b32_e64 v112, -v231, v230, vcc
	v_mul_f32_e32 v112, v112, v113
	v_exp_f32_e32 v112, v112
	v_cmp_ne_u32_e32 vcc, v232, v163
	s_lshl_b32 s16, s47, 15
	s_add_u32 s16, s4, s16
	v_cndmask_b32_e32 v103, 2.0, v112, vcc
	v_cmp_ne_u32_e32 vcc, v229, v180
	v_sub_u32_e32 v112, v233, v180
	v_cvt_f32_i32_e32 v113, v112
	v_cndmask_b32_e32 v102, 2.0, v102, vcc
	v_pk_mul_f32 v[102:103], v[104:105], v[102:103]
	v_sub_u32_e32 v104, v234, v180
	v_cmp_lt_i32_e32 vcc, 0, v104
	v_cvt_f32_i32_e32 v104, v104
	v_cvt_pk_bf16_f32 v102, v102, v103
	v_cndmask_b32_e64 v105, -v231, v230, vcc
	v_cmp_lt_i32_e32 vcc, 0, v112
	v_mul_f32_e32 v104, v105, v104
	v_exp_f32_e32 v104, v104
	v_cndmask_b32_e64 v112, -v231, v230, vcc
	v_mul_f32_e32 v112, v112, v113
	v_exp_f32_e32 v112, v112
	v_cmp_ne_u32_e32 vcc, v233, v163
	s_addc_u32 s17, s17, 0
	global_load_dwordx4 v[0:3], v198, s[16:17]
	global_load_dwordx4 v[4:7], v206, s[16:17]
	global_load_dwordx4 v[8:11], v208, s[16:17]
	global_load_dwordx4 v[12:15], v210, s[16:17]
	s_nop 0
	v_cndmask_b32_e32 v105, 2.0, v112, vcc
	v_cmp_ne_u32_e32 vcc, v234, v180
	s_nop 1
	v_cndmask_b32_e32 v104, 2.0, v104, vcc
	v_pk_mul_f32 v[104:105], v[106:107], v[104:105]
	s_nop 0
	v_cvt_pk_bf16_f32 v103, v104, v105
	ds_write2_b64 v205, v[100:101], v[102:103] offset1:80
	v_sub_u32_e32 v102, v232, v182
	v_sub_u32_e32 v100, v229, v182
	v_cvt_f32_i32_e32 v103, v102
	v_cmp_lt_i32_e32 vcc, 0, v100
	v_cvt_f32_i32_e32 v100, v100
	v_sub_u32_e32 v104, v233, v182
	v_cndmask_b32_e64 v101, -v231, v230, vcc
	v_cmp_lt_i32_e32 vcc, 0, v102
	v_mul_f32_e32 v100, v101, v100
	v_exp_f32_e32 v100, v100
	v_cndmask_b32_e64 v102, -v231, v230, vcc
	v_mul_f32_e32 v102, v102, v103
	v_exp_f32_e32 v102, v102
	v_cmp_ne_u32_e32 vcc, v232, v165
	v_cvt_f32_i32_e32 v105, v104
	s_nop 0
	v_cndmask_b32_e32 v101, 2.0, v102, vcc
	v_cmp_ne_u32_e32 vcc, v229, v182
	v_sub_u32_e32 v102, v234, v182
	s_nop 0
	v_cndmask_b32_e32 v100, 2.0, v100, vcc
	v_cmp_lt_i32_e32 vcc, 0, v102
	v_cvt_f32_i32_e32 v102, v102
	v_pk_mul_f32 v[100:101], v[108:109], v[100:101]
	v_cndmask_b32_e64 v103, -v231, v230, vcc
	v_cmp_lt_i32_e32 vcc, 0, v104
	v_mul_f32_e32 v102, v103, v102
	v_exp_f32_e32 v102, v102
	v_cndmask_b32_e64 v104, -v231, v230, vcc
	v_mul_f32_e32 v104, v104, v105
	v_exp_f32_e32 v104, v104
	v_cmp_ne_u32_e32 vcc, v233, v165
	v_cvt_pk_bf16_f32 v100, v100, v101
	s_nop 0
	v_cndmask_b32_e32 v103, 2.0, v104, vcc
	v_cmp_ne_u32_e32 vcc, v234, v182
	v_sub_u32_e32 v104, v232, v184
	v_cvt_f32_i32_e32 v105, v104
	v_cndmask_b32_e32 v102, 2.0, v102, vcc
	v_pk_mul_f32 v[102:103], v[110:111], v[102:103]
	s_nop 0
	v_cvt_pk_bf16_f32 v101, v102, v103
	v_sub_u32_e32 v102, v229, v184
	v_cmp_lt_i32_e32 vcc, 0, v102
	v_cvt_f32_i32_e32 v102, v102
	s_nop 0
	v_cndmask_b32_e64 v103, -v231, v230, vcc
	v_cmp_lt_i32_e32 vcc, 0, v104
	v_mul_f32_e32 v102, v103, v102
	v_exp_f32_e32 v102, v102
	v_cndmask_b32_e64 v104, -v231, v230, vcc
	v_mul_f32_e32 v104, v104, v105
	v_exp_f32_e32 v104, v104
	v_cmp_ne_u32_e32 vcc, v232, v169
	s_nop 1
	v_cndmask_b32_e32 v103, 2.0, v104, vcc
	v_cmp_ne_u32_e32 vcc, v229, v184
	v_sub_u32_e32 v104, v233, v184
	v_cvt_f32_i32_e32 v105, v104
	v_cndmask_b32_e32 v102, 2.0, v102, vcc
	v_pk_mul_f32 v[96:97], v[96:97], v[102:103]
	v_sub_u32_e32 v102, v234, v184
	v_cmp_lt_i32_e32 vcc, 0, v102
	v_cvt_f32_i32_e32 v102, v102
	v_cvt_pk_bf16_f32 v96, v96, v97
	v_cndmask_b32_e64 v103, -v231, v230, vcc
	v_cmp_lt_i32_e32 vcc, 0, v104
	v_mul_f32_e32 v102, v103, v102
	v_exp_f32_e32 v102, v102
	v_cndmask_b32_e64 v104, -v231, v230, vcc
	v_mul_f32_e32 v104, v104, v105
	v_exp_f32_e32 v104, v104
	v_cmp_ne_u32_e32 vcc, v233, v169
	s_nop 1
	v_cndmask_b32_e32 v103, 2.0, v104, vcc
	v_cmp_ne_u32_e32 vcc, v234, v184
	s_nop 1
	v_cndmask_b32_e32 v102, 2.0, v102, vcc
	v_pk_mul_f32 v[98:99], v[98:99], v[102:103]
	s_nop 0
	v_cvt_pk_bf16_f32 v97, v98, v99
	v_sub_u32_e32 v98, v232, v186
	ds_write2_b64 v205, v[100:101], v[96:97] offset0:160 offset1:240
	v_sub_u32_e32 v96, v229, v186
	v_cvt_f32_i32_e32 v99, v98
	v_cmp_lt_i32_e32 vcc, 0, v96
	v_cvt_f32_i32_e32 v96, v96
	s_nop 0
	v_cndmask_b32_e64 v97, -v231, v230, vcc
	v_cmp_lt_i32_e32 vcc, 0, v98
	v_mul_f32_e32 v96, v97, v96
	v_exp_f32_e32 v96, v96
	v_cndmask_b32_e64 v98, -v231, v230, vcc
	v_mul_f32_e32 v98, v98, v99
	v_exp_f32_e32 v98, v98
	v_cmp_ne_u32_e32 vcc, v232, v175
	s_nop 1
	v_cndmask_b32_e32 v97, 2.0, v98, vcc
	v_cmp_ne_u32_e32 vcc, v229, v186
	v_sub_u32_e32 v98, v233, v186
	v_cvt_f32_i32_e32 v99, v98
	v_cndmask_b32_e32 v96, 2.0, v96, vcc
	v_pk_mul_f32 v[92:93], v[96:97], v[92:93]
	v_sub_u32_e32 v96, v234, v186
	v_cmp_lt_i32_e32 vcc, 0, v96
	v_cvt_f32_i32_e32 v96, v96
	v_cvt_pk_bf16_f32 v92, v92, v93
	v_cndmask_b32_e64 v97, -v231, v230, vcc
	v_cmp_lt_i32_e32 vcc, 0, v98
	v_mul_f32_e32 v96, v97, v96
	v_exp_f32_e32 v96, v96
	v_cndmask_b32_e64 v98, -v231, v230, vcc
	v_mul_f32_e32 v98, v98, v99
	v_exp_f32_e32 v98, v98
	v_cmp_ne_u32_e32 vcc, v233, v175
	s_nop 1
	v_cndmask_b32_e32 v97, 2.0, v98, vcc
	v_cmp_ne_u32_e32 vcc, v234, v186
	s_nop 1
	v_cndmask_b32_e32 v96, 2.0, v96, vcc
	v_pk_mul_f32 v[94:95], v[96:97], v[94:95]
	v_sub_u32_e32 v96, v232, v188
	v_cvt_pk_bf16_f32 v93, v94, v95
	v_sub_u32_e32 v94, v229, v188
	v_cvt_f32_i32_e32 v97, v96
	v_cmp_lt_i32_e32 vcc, 0, v94
	v_cvt_f32_i32_e32 v94, v94
	s_nop 0
	v_cndmask_b32_e64 v95, -v231, v230, vcc
	v_cmp_lt_i32_e32 vcc, 0, v96
	v_mul_f32_e32 v94, v95, v94
	v_exp_f32_e32 v94, v94
	v_cndmask_b32_e64 v96, -v231, v230, vcc
	v_mul_f32_e32 v96, v96, v97
	v_exp_f32_e32 v96, v96
	v_cmp_ne_u32_e32 vcc, v232, v177
	s_nop 1
	v_cndmask_b32_e32 v95, 2.0, v96, vcc
	v_cmp_ne_u32_e32 vcc, v229, v188
	v_sub_u32_e32 v96, v233, v188
	v_cvt_f32_i32_e32 v97, v96
	v_cndmask_b32_e32 v94, 2.0, v94, vcc
	v_pk_mul_f32 v[88:89], v[94:95], v[88:89]
	v_sub_u32_e32 v94, v234, v188
	v_cmp_lt_i32_e32 vcc, 0, v94
	v_cvt_f32_i32_e32 v94, v94
	v_cvt_pk_bf16_f32 v88, v88, v89
	v_cndmask_b32_e64 v95, -v231, v230, vcc
	v_cmp_lt_i32_e32 vcc, 0, v96
	v_mul_f32_e32 v94, v95, v94
	v_exp_f32_e32 v94, v94
	v_cndmask_b32_e64 v96, -v231, v230, vcc
	v_mul_f32_e32 v96, v96, v97
	v_exp_f32_e32 v96, v96
	v_cmp_ne_u32_e32 vcc, v233, v177
	s_nop 1
	v_cndmask_b32_e32 v95, 2.0, v96, vcc
	v_cmp_ne_u32_e32 vcc, v234, v188
	v_add_u32_e32 v96, 0, v168
	s_nop 0
	v_cndmask_b32_e32 v94, 2.0, v94, vcc
	v_pk_mul_f32 v[90:91], v[94:95], v[90:91]
	s_nop 0
	v_cvt_pk_bf16_f32 v89, v90, v91
	v_add_u32_e32 v90, 0x800, v205
	ds_write2_b64 v90, v[92:93], v[88:89] offset0:64 offset1:144
	v_sub_u32_e32 v90, v232, v190
	v_sub_u32_e32 v88, v229, v190
	v_cvt_f32_i32_e32 v91, v90
	v_cmp_lt_i32_e32 vcc, 0, v88
	v_cvt_f32_i32_e32 v88, v88
	s_nop 0
	v_cndmask_b32_e64 v89, -v231, v230, vcc
	v_cmp_lt_i32_e32 vcc, 0, v90
	v_mul_f32_e32 v88, v89, v88
	v_exp_f32_e32 v88, v88
	v_cndmask_b32_e64 v90, -v231, v230, vcc
	v_mul_f32_e32 v90, v90, v91
	v_exp_f32_e32 v90, v90
	v_cmp_ne_u32_e32 vcc, v232, v181
	s_nop 1
	v_cndmask_b32_e32 v89, 2.0, v90, vcc
	v_cmp_ne_u32_e32 vcc, v229, v190
	v_sub_u32_e32 v90, v233, v190
	v_cvt_f32_i32_e32 v91, v90
	v_cndmask_b32_e32 v88, 2.0, v88, vcc
	v_pk_mul_f32 v[84:85], v[88:89], v[84:85]
	v_sub_u32_e32 v88, v234, v190
	v_cmp_lt_i32_e32 vcc, 0, v88
	v_cvt_f32_i32_e32 v88, v88
	v_cvt_pk_bf16_f32 v84, v84, v85
	v_cndmask_b32_e64 v89, -v231, v230, vcc
	v_cmp_lt_i32_e32 vcc, 0, v90
	v_mul_f32_e32 v88, v89, v88
	v_exp_f32_e32 v88, v88
	v_cndmask_b32_e64 v90, -v231, v230, vcc
	v_mul_f32_e32 v90, v90, v91
	v_exp_f32_e32 v90, v90
	v_cmp_ne_u32_e32 vcc, v233, v181
	s_nop 1
	v_cndmask_b32_e32 v89, 2.0, v90, vcc
	v_cmp_ne_u32_e32 vcc, v234, v190
	s_nop 1
	v_cndmask_b32_e32 v88, 2.0, v88, vcc
	v_pk_mul_f32 v[86:87], v[88:89], v[86:87]
	v_sub_u32_e32 v88, v232, v192
	v_cvt_pk_bf16_f32 v85, v86, v87
	v_sub_u32_e32 v86, v229, v192
	v_cvt_f32_i32_e32 v89, v88
	v_cmp_lt_i32_e32 vcc, 0, v86
	v_cvt_f32_i32_e32 v86, v86
	s_nop 0
	v_cndmask_b32_e64 v87, -v231, v230, vcc
	v_cmp_lt_i32_e32 vcc, 0, v88
	v_mul_f32_e32 v86, v87, v86
	v_exp_f32_e32 v86, v86
	v_cndmask_b32_e64 v88, -v231, v230, vcc
	v_mul_f32_e32 v88, v88, v89
	v_exp_f32_e32 v88, v88
	v_cmp_ne_u32_e32 vcc, v232, v183
	s_nop 1
	v_cndmask_b32_e32 v87, 2.0, v88, vcc
	v_cmp_ne_u32_e32 vcc, v229, v192
	v_sub_u32_e32 v88, v233, v192
	v_cvt_f32_i32_e32 v89, v88
	v_cndmask_b32_e32 v86, 2.0, v86, vcc
	v_pk_mul_f32 v[80:81], v[86:87], v[80:81]
	v_sub_u32_e32 v86, v234, v192
	v_cmp_lt_i32_e32 vcc, 0, v86
	v_cvt_f32_i32_e32 v86, v86
	v_cvt_pk_bf16_f32 v80, v80, v81
	v_cndmask_b32_e64 v87, -v231, v230, vcc
	v_cmp_lt_i32_e32 vcc, 0, v88
	v_mul_f32_e32 v86, v87, v86
	v_exp_f32_e32 v86, v86
	v_cndmask_b32_e64 v88, -v231, v230, vcc
	v_mul_f32_e32 v88, v88, v89
	v_exp_f32_e32 v88, v88
	v_cmp_ne_u32_e32 vcc, v233, v183
	s_nop 1
	v_cndmask_b32_e32 v87, 2.0, v88, vcc
	v_cmp_ne_u32_e32 vcc, v234, v192
	s_nop 1
	v_cndmask_b32_e32 v86, 2.0, v86, vcc
	v_pk_mul_f32 v[82:83], v[86:87], v[82:83]
	s_nop 0
	v_cvt_pk_bf16_f32 v81, v82, v83
	v_add_u32_e32 v82, 0xc00, v205
	ds_write2_b64 v82, v[84:85], v[80:81] offset0:96 offset1:176
	s_waitcnt lgkmcnt(0)
	s_barrier
	s_waitcnt vmcnt(0)
	ds_write_b128 v96, v[0:3]
	ds_write_b128 v207, v[4:7]
	ds_write_b128 v209, v[8:11]
	ds_write_b128 v211, v[12:15]
	ds_read_b64_tr_b16 v[80:81], v212
	ds_read_b64_tr_b16 v[82:83], v212 offset:160
	ds_read_b64_tr_b16 v[86:87], v213 offset:40128
	ds_read_b64_tr_b16 v[84:85], v213 offset:38912
	ds_read_b64_tr_b16 v[88:89], v213 offset:38944
	ds_read_b64_tr_b16 v[90:91], v213 offset:40160
	ds_read_b64_tr_b16 v[92:93], v213 offset:39136
	ds_read_b64_tr_b16 v[96:97], v213 offset:40192
	ds_read_b64_tr_b16 v[94:95], v213 offset:38976
	ds_read_b64_tr_b16 v[98:99], v213 offset:39008
	ds_read_b64_tr_b16 v[102:103], v213 offset:39040
	ds_read_b64_tr_b16 v[106:107], v213 offset:39072
	ds_read_b64_tr_b16 v[100:101], v213 offset:40224
	ds_read_b64_tr_b16 v[104:105], v213 offset:40256
	ds_read_b64_tr_b16 v[108:109], v213 offset:40288
	s_waitcnt lgkmcnt(6)
	v_mfma_f32_16x16x32_bf16 v[110:113], v[80:83], v[94:97], 0
	s_waitcnt lgkmcnt(2)
	v_mfma_f32_16x16x32_bf16 v[96:99], v[80:83], v[98:101], 0
	s_waitcnt lgkmcnt(1)
	v_mfma_f32_16x16x32_bf16 v[100:103], v[80:83], v[102:105], 0
	ds_read_b64_tr_b16 v[104:105], v213 offset:39104
	s_waitcnt lgkmcnt(1)
	v_mfma_f32_16x16x32_bf16 v[114:117], v[80:83], v[106:109], 0
	ds_read_b64_tr_b16 v[106:107], v213 offset:40320
	ds_read_b64_tr_b16 v[94:95], v213 offset:40352
	v_mfma_f32_16x16x32_bf16 v[84:87], v[80:83], v[84:87], 0
	v_mfma_f32_16x16x32_bf16 v[88:91], v[80:83], v[88:91], 0
	s_waitcnt lgkmcnt(1)
	v_mfma_f32_16x16x32_bf16 v[104:107], v[80:83], v[104:107], 0
	s_waitcnt lgkmcnt(0)
	v_mfma_f32_16x16x32_bf16 v[80:83], v[80:83], v[92:95], 0
	ds_read_b64_tr_b16 v[92:93], v212 offset:1280
	ds_read_b64_tr_b16 v[94:95], v212 offset:1440
	ds_read_b64_tr_b16 v[120:121], v213 offset:49856
	ds_read_b64_tr_b16 v[118:119], v213 offset:48640
	ds_read_b64_tr_b16 v[122:123], v213 offset:48672
	ds_read_b64_tr_b16 v[124:125], v213 offset:49888
	ds_read_b64_tr_b16 v[108:109], v213 offset:48864
	s_waitcnt lgkmcnt(3)
	v_mfma_f32_16x16x32_bf16 v[84:87], v[92:95], v[118:121], v[84:87]
	ds_read_b64_tr_b16 v[120:121], v213 offset:49920
	s_waitcnt lgkmcnt(2)
	v_mfma_f32_16x16x32_bf16 v[88:91], v[92:95], v[122:125], v[88:91]
	ds_read_b64_tr_b16 v[118:119], v213 offset:48704
	ds_read_b64_tr_b16 v[122:123], v213 offset:48736
	ds_read_b64_tr_b16 v[126:127], v213 offset:48768
	ds_read_b64_tr_b16 v[130:131], v213 offset:48800
	ds_read_b64_tr_b16 v[124:125], v213 offset:49952
	ds_read_b64_tr_b16 v[128:129], v213 offset:49984
	ds_read_b64_tr_b16 v[132:133], v213 offset:50016
	s_waitcnt lgkmcnt(6)
	v_mfma_f32_16x16x32_bf16 v[118:121], v[92:95], v[118:121], v[110:113]
	s_waitcnt lgkmcnt(2)
	v_mfma_f32_16x16x32_bf16 v[96:99], v[92:95], v[122:125], v[96:99]
	s_nop 0
	ds_read_b64_tr_b16 v[112:113], v213 offset:48832
	s_waitcnt lgkmcnt(1)
	v_mfma_f32_16x16x32_bf16 v[122:125], v[92:95], v[130:133], v[114:117]
	s_nop 2
	ds_read_b64_tr_b16 v[114:115], v213 offset:50048
	ds_read_b64_tr_b16 v[110:111], v213 offset:50080
	v_mfma_f32_16x16x32_bf16 v[100:103], v[92:95], v[126:129], v[100:103]
	s_waitcnt lgkmcnt(1)
	v_mfma_f32_16x16x32_bf16 v[104:107], v[92:95], v[112:115], v[104:107]
	s_waitcnt lgkmcnt(0)
	v_mfma_f32_16x16x32_bf16 v[80:83], v[92:95], v[108:111], v[80:83]
	ds_read_b64_tr_b16 v[92:93], v212 offset:2560
	ds_read_b64_tr_b16 v[94:95], v212 offset:2720
	ds_read_b64_tr_b16 v[110:111], v213 offset:59584
	ds_read_b64_tr_b16 v[108:109], v213 offset:58368
	ds_read_b64_tr_b16 v[112:113], v213 offset:58400
	ds_read_b64_tr_b16 v[114:115], v213 offset:59616
	ds_read_b64_tr_b16 v[116:117], v213 offset:58592
	s_waitcnt lgkmcnt(3)
	v_mfma_f32_16x16x32_bf16 v[84:87], v[92:95], v[108:111], v[84:87]
	ds_read_b64_tr_b16 v[110:111], v213 offset:59648
	s_waitcnt lgkmcnt(2)
	v_mfma_f32_16x16x32_bf16 v[88:91], v[92:95], v[112:115], v[88:91]
	ds_read_b64_tr_b16 v[108:109], v213 offset:58432
	ds_read_b64_tr_b16 v[112:113], v213 offset:58464
	ds_read_b64_tr_b16 v[126:127], v213 offset:58496
	ds_read_b64_tr_b16 v[130:131], v213 offset:58528
	ds_read_b64_tr_b16 v[114:115], v213 offset:59680
	ds_read_b64_tr_b16 v[128:129], v213 offset:59712
	ds_read_b64_tr_b16 v[132:133], v213 offset:59744
	s_waitcnt lgkmcnt(6)
	v_mfma_f32_16x16x32_bf16 v[134:137], v[92:95], v[108:111], v[118:121]
	s_waitcnt lgkmcnt(2)
	v_mfma_f32_16x16x32_bf16 v[112:115], v[92:95], v[112:115], v[96:99]
	s_nop 2
	ds_read_b64_tr_b16 v[96:97], v213 offset:58560
	ds_read_b64_tr_b16 v[98:99], v213 offset:59776
	ds_read_b64_tr_b16 v[118:119], v213 offset:59808
	s_waitcnt lgkmcnt(4)
	v_mfma_f32_16x16x32_bf16 v[126:129], v[92:95], v[126:129], v[100:103]
	s_waitcnt lgkmcnt(3)
	v_mfma_f32_16x16x32_bf16 v[120:123], v[92:95], v[130:133], v[122:125]
	s_waitcnt lgkmcnt(1)
	v_mfma_f32_16x16x32_bf16 v[130:133], v[92:95], v[96:99], v[104:107]
	s_waitcnt lgkmcnt(0)
	v_mfma_f32_16x16x32_bf16 v[116:119], v[92:95], v[116:119], v[80:83]
	ds_read_b64_tr_b16 v[138:139], v212 offset:3840
	ds_read_b64_tr_b16 v[140:141], v212 offset:4000
	s_nop 0
	ds_read_b64_tr_b16 v[82:83], v214 offset:59584
	ds_read_b64_tr_b16 v[80:81], v214 offset:58368
	ds_read_b64_tr_b16 v[92:93], v214 offset:58400
	ds_read_b64_tr_b16 v[94:95], v214 offset:59616
	ds_read_b64_tr_b16 v[124:125], v214 offset:58592
	s_waitcnt lgkmcnt(3)
	v_mfma_f32_16x16x32_bf16 v[108:111], v[138:141], v[80:83], v[84:87]
	ds_read_b64_tr_b16 v[82:83], v214 offset:59648
	s_waitcnt lgkmcnt(2)
	v_mfma_f32_16x16x32_bf16 v[104:107], v[138:141], v[92:95], v[88:91]
	ds_read_b64_tr_b16 v[80:81], v214 offset:58432
	ds_read_b64_tr_b16 v[84:85], v214 offset:58464
	s_nop 0
	ds_read_b64_tr_b16 v[88:89], v214 offset:58496
	ds_read_b64_tr_b16 v[92:93], v214 offset:58528
	ds_read_b64_tr_b16 v[86:87], v214 offset:59680
	ds_read_b64_tr_b16 v[90:91], v214 offset:59712
	ds_read_b64_tr_b16 v[94:95], v214 offset:59744
	s_waitcnt lgkmcnt(6)
	v_mfma_f32_16x16x32_bf16 v[96:99], v[138:141], v[80:83], v[134:137]
	ds_read_b64_tr_b16 v[80:81], v214 offset:58560
	s_waitcnt lgkmcnt(2)
	v_mfma_f32_16x16x32_bf16 v[88:91], v[138:141], v[88:91], v[126:129]
	ds_read_b64_tr_b16 v[82:83], v214 offset:59776
	s_nop 1
	ds_read_b64_tr_b16 v[126:127], v214 offset:59808
	v_mfma_f32_16x16x32_bf16 v[100:103], v[138:141], v[84:87], v[112:115]
	s_waitcnt lgkmcnt(3)
	v_mfma_f32_16x16x32_bf16 v[92:95], v[138:141], v[92:95], v[120:123]
	s_waitcnt lgkmcnt(1)
	v_mfma_f32_16x16x32_bf16 v[80:83], v[138:141], v[80:83], v[130:133]
	s_waitcnt lgkmcnt(0)
	v_mfma_f32_16x16x32_bf16 v[84:87], v[138:141], v[124:127], v[116:119]
	v_add_u32_e32 v112, s42, v187
	ds_read_b128 v[112:115], v112
	v_add_u32_e32 v199, 0, v187
	v_add_u32_e32 v116, 0x13400, v199
	ds_read_b128 v[116:119], v116
	v_add_u32_e32 v120, 0x13800, v199
	s_waitcnt lgkmcnt(1)
	v_mfma_f32_16x16x32_bf16 v[112:115], v[44:47], v[112:115], 0
	s_waitcnt lgkmcnt(0)
	v_mfma_f32_16x16x32_bf16 v[112:115], v[48:51], v[116:119], v[112:115]
	ds_read_b128 v[116:119], v120
	v_add_u32_e32 v120, 0x13c00, v199
	ds_read_b128 v[120:123], v120
	s_waitcnt lgkmcnt(1)
	v_mfma_f32_16x16x32_bf16 v[112:115], v[52:55], v[116:119], v[112:115]
	v_add_u32_e32 v116, 0x14000, v199
	s_waitcnt lgkmcnt(0)
	v_mfma_f32_16x16x32_bf16 v[136:139], v[60:63], v[120:123], v[112:115]
	v_add_u32_e32 v120, 0x14800, v199
	s_nop 3
	ds_read_b128 v[112:115], v116
	v_add_u32_e32 v116, 0x14400, v199
	ds_read_b128 v[116:119], v116
	s_waitcnt lgkmcnt(1)
	v_mfma_f32_16x16x32_bf16 v[112:115], v[44:47], v[112:115], 0
	s_waitcnt lgkmcnt(0)
	v_mfma_f32_16x16x32_bf16 v[112:115], v[48:51], v[116:119], v[112:115]
	ds_read_b128 v[116:119], v120
	v_add_u32_e32 v120, 0x14c00, v199
	s_waitcnt lgkmcnt(0)
	v_mfma_f32_16x16x32_bf16 v[112:115], v[52:55], v[116:119], v[112:115]
	ds_read_b128 v[116:119], v120
	s_waitcnt lgkmcnt(0)
	v_mfma_f32_16x16x32_bf16 v[140:143], v[60:63], v[116:119], v[112:115]
	s_nop 4
	v_add_u32_e32 v112, 0x15000, v199
	ds_read_b128 v[112:115], v112
	v_add_u32_e32 v116, 0x15400, v199
	ds_read_b128 v[116:119], v116
	v_add_u32_e32 v120, 0x15800, v199
	s_waitcnt lgkmcnt(1)
	v_mfma_f32_16x16x32_bf16 v[112:115], v[44:47], v[112:115], 0
	s_waitcnt lgkmcnt(0)
	v_mfma_f32_16x16x32_bf16 v[112:115], v[48:51], v[116:119], v[112:115]
	ds_read_b128 v[116:119], v120
	v_add_u32_e32 v120, 0x15c00, v199
	ds_read_b128 v[120:123], v120
	s_waitcnt lgkmcnt(1)
	v_mfma_f32_16x16x32_bf16 v[112:115], v[52:55], v[116:119], v[112:115]
	v_add_u32_e32 v116, 0x16000, v199
	s_waitcnt lgkmcnt(0)
	v_mfma_f32_16x16x32_bf16 v[124:127], v[60:63], v[120:123], v[112:115]
	v_add_u32_e32 v120, 0x16800, v199
	s_nop 3
	ds_read_b128 v[112:115], v116
	v_add_u32_e32 v116, 0x16400, v199
	ds_read_b128 v[116:119], v116
	s_waitcnt lgkmcnt(1)
	v_mfma_f32_16x16x32_bf16 v[112:115], v[44:47], v[112:115], 0
	s_waitcnt lgkmcnt(0)
	v_mfma_f32_16x16x32_bf16 v[112:115], v[48:51], v[116:119], v[112:115]
	ds_read_b128 v[116:119], v120
	v_add_u32_e32 v120, 0x16c00, v199
	s_waitcnt lgkmcnt(0)
	v_mfma_f32_16x16x32_bf16 v[112:115], v[52:55], v[116:119], v[112:115]
	ds_read_b128 v[116:119], v120
	s_waitcnt lgkmcnt(0)
	v_mfma_f32_16x16x32_bf16 v[132:135], v[60:63], v[116:119], v[112:115]
	s_nop 4
	v_add_u32_e32 v112, 0x17000, v199
	ds_read_b128 v[112:115], v112
	v_add_u32_e32 v116, 0x17400, v199
	ds_read_b128 v[116:119], v116
	v_add_u32_e32 v120, 0x17800, v199
	v_add_u32_e32 v128, 0x18000, v199
	s_waitcnt lgkmcnt(1)
	v_mfma_f32_16x16x32_bf16 v[112:115], v[44:47], v[112:115], 0
	s_waitcnt lgkmcnt(0)
	v_mfma_f32_16x16x32_bf16 v[112:115], v[48:51], v[116:119], v[112:115]
	ds_read_b128 v[116:119], v120
	v_add_u32_e32 v120, 0x17c00, v199
	ds_read_b128 v[120:123], v120
	s_waitcnt lgkmcnt(1)
	v_mfma_f32_16x16x32_bf16 v[112:115], v[52:55], v[116:119], v[112:115]
	s_waitcnt lgkmcnt(0)
	v_mfma_f32_16x16x32_bf16 v[116:119], v[60:63], v[120:123], v[112:115]
	v_add_u32_e32 v120, 0x18400, v199
	ds_read_b128 v[120:123], v120
	s_nop 3
	ds_read_b128 v[112:115], v128
	s_waitcnt lgkmcnt(0)
	v_mfma_f32_16x16x32_bf16 v[112:115], v[44:47], v[112:115], 0
	v_add_u32_e32 v128, 0x18800, v199
	v_mfma_f32_16x16x32_bf16 v[112:115], v[48:51], v[120:123], v[112:115]
	ds_read_b128 v[120:123], v128
	v_add_u32_e32 v128, 0x18c00, v199
	s_waitcnt lgkmcnt(0)
	v_mfma_f32_16x16x32_bf16 v[112:115], v[52:55], v[120:123], v[112:115]
	ds_read_b128 v[120:123], v128
	s_waitcnt lgkmcnt(0)
	v_mfma_f32_16x16x32_bf16 v[128:131], v[60:63], v[120:123], v[112:115]
	s_nop 4
	v_add_u32_e32 v112, 0x19000, v199
	ds_read_b128 v[112:115], v112
	v_add_u32_e32 v120, 0x19400, v199
	ds_read_b128 v[120:123], v120
	v_add_u32_e32 v144, 0x19800, v199
	v_add_u32_e32 v148, 0x1a800, v199
	s_waitcnt lgkmcnt(1)
	v_mfma_f32_16x16x32_bf16 v[112:115], v[44:47], v[112:115], 0
	s_waitcnt lgkmcnt(0)
	v_mfma_f32_16x16x32_bf16 v[112:115], v[48:51], v[120:123], v[112:115]
	ds_read_b128 v[120:123], v144
	v_add_u32_e32 v144, 0x19c00, v199
	ds_read_b128 v[144:147], v144
	s_waitcnt lgkmcnt(1)
	v_mfma_f32_16x16x32_bf16 v[112:115], v[52:55], v[120:123], v[112:115]
	v_add_u32_e32 v120, 0x1a000, v199
	ds_read_b128 v[120:123], v120
	s_waitcnt lgkmcnt(1)
	v_mfma_f32_16x16x32_bf16 v[112:115], v[60:63], v[144:147], v[112:115]
	v_add_u32_e32 v144, 0x1a400, v199
	ds_read_b128 v[144:147], v144
	s_waitcnt lgkmcnt(1)
	v_mfma_f32_16x16x32_bf16 v[120:123], v[44:47], v[120:123], 0
	s_waitcnt lgkmcnt(0)
	v_mfma_f32_16x16x32_bf16 v[120:123], v[48:51], v[144:147], v[120:123]
	ds_read_b128 v[144:147], v148
	v_add_u32_e32 v148, 0x1ac00, v199
	s_waitcnt lgkmcnt(0)
	v_mfma_f32_16x16x32_bf16 v[120:123], v[52:55], v[144:147], v[120:123]
	ds_read_b128 v[144:147], v148
	s_waitcnt lgkmcnt(0)
	v_mfma_f32_16x16x32_bf16 v[120:123], v[60:63], v[144:147], v[120:123]
	s_waitcnt lgkmcnt(0)
	s_barrier
	ds_write_b128 v220, v[64:67]
	ds_write_b128 v221, v[68:71]
	ds_write_b128 v221, v[72:75] offset:8704
	ds_write_b128 v221, v[76:79] offset:17408
	ds_read_b128 v[64:67], v199
	ds_read_b128 v[68:71], v199 offset:1024
	s_waitcnt lgkmcnt(1)
	v_mfma_f32_16x16x32_bf16 v[64:67], v[44:47], v[64:67], 0
	s_waitcnt lgkmcnt(0)
	v_mfma_f32_16x16x32_bf16 v[64:67], v[48:51], v[68:71], v[64:67]
	ds_read_b128 v[68:71], v199 offset:2048
	ds_read_b128 v[72:75], v199 offset:3072
	s_waitcnt lgkmcnt(1)
	v_mfma_f32_16x16x32_bf16 v[64:67], v[52:55], v[68:71], v[64:67]
	ds_read_b128 v[68:71], v199 offset:5120
	s_waitcnt lgkmcnt(1)
	v_mfma_f32_16x16x32_bf16 v[152:155], v[60:63], v[72:75], v[64:67]
	s_nop 4
	ds_read_b128 v[64:67], v199 offset:4096
	s_waitcnt lgkmcnt(0)
	v_mfma_f32_16x16x32_bf16 v[64:67], v[44:47], v[64:67], 0
	v_mfma_f32_16x16x32_bf16 v[64:67], v[48:51], v[68:71], v[64:67]
	ds_read_b128 v[68:71], v199 offset:6144
	s_waitcnt lgkmcnt(0)
	v_mfma_f32_16x16x32_bf16 v[64:67], v[52:55], v[68:71], v[64:67]
	ds_read_b128 v[68:71], v199 offset:7168
	s_waitcnt lgkmcnt(0)
	v_mfma_f32_16x16x32_bf16 v[156:159], v[60:63], v[68:71], v[64:67]
	s_nop 4
	ds_read_b128 v[64:67], v199 offset:8192
	ds_read_b128 v[68:71], v199 offset:9216
	s_waitcnt lgkmcnt(1)
	v_mfma_f32_16x16x32_bf16 v[64:67], v[44:47], v[64:67], 0
	s_waitcnt lgkmcnt(0)
	v_mfma_f32_16x16x32_bf16 v[64:67], v[48:51], v[68:71], v[64:67]
	ds_read_b128 v[68:71], v199 offset:10240
	ds_read_b128 v[72:75], v199 offset:11264
	s_waitcnt lgkmcnt(1)
	v_mfma_f32_16x16x32_bf16 v[64:67], v[52:55], v[68:71], v[64:67]
	ds_read_b128 v[68:71], v199 offset:13312
	s_waitcnt lgkmcnt(1)
	v_mfma_f32_16x16x32_bf16 v[144:147], v[60:63], v[72:75], v[64:67]
	s_nop 4
	ds_read_b128 v[64:67], v199 offset:12288
	s_waitcnt lgkmcnt(0)
	v_mfma_f32_16x16x32_bf16 v[64:67], v[44:47], v[64:67], 0
	v_mfma_f32_16x16x32_bf16 v[64:67], v[48:51], v[68:71], v[64:67]
	ds_read_b128 v[68:71], v199 offset:14336
	s_waitcnt lgkmcnt(0)
	v_mfma_f32_16x16x32_bf16 v[64:67], v[52:55], v[68:71], v[64:67]
	ds_read_b128 v[68:71], v199 offset:15360
	s_waitcnt lgkmcnt(0)
	v_mfma_f32_16x16x32_bf16 v[148:151], v[60:63], v[68:71], v[64:67]
	s_nop 4
	ds_read_b128 v[64:67], v199 offset:16384
	ds_read_b128 v[68:71], v199 offset:17408
	s_waitcnt lgkmcnt(1)
	v_mfma_f32_16x16x32_bf16 v[64:67], v[44:47], v[64:67], 0
	s_waitcnt lgkmcnt(0)
	v_mfma_f32_16x16x32_bf16 v[64:67], v[48:51], v[68:71], v[64:67]
	ds_read_b128 v[68:71], v199 offset:18432
	ds_read_b128 v[72:75], v199 offset:19456
	s_waitcnt lgkmcnt(1)
	v_mfma_f32_16x16x32_bf16 v[64:67], v[52:55], v[68:71], v[64:67]
	ds_read_b128 v[68:71], v199 offset:21504
	s_waitcnt lgkmcnt(1)
	v_mfma_f32_16x16x32_bf16 v[72:75], v[60:63], v[72:75], v[64:67]
	s_nop 4
	ds_read_b128 v[64:67], v199 offset:20480
	s_waitcnt lgkmcnt(0)
	v_mfma_f32_16x16x32_bf16 v[64:67], v[44:47], v[64:67], 0
	v_mfma_f32_16x16x32_bf16 v[64:67], v[48:51], v[68:71], v[64:67]
	ds_read_b128 v[68:71], v199 offset:22528
	s_waitcnt lgkmcnt(0)
	v_mfma_f32_16x16x32_bf16 v[64:67], v[52:55], v[68:71], v[64:67]
	ds_read_b128 v[68:71], v199 offset:23552
	s_waitcnt lgkmcnt(0)
	v_mfma_f32_16x16x32_bf16 v[76:79], v[60:63], v[68:71], v[64:67]
	s_nop 4
	ds_read_b128 v[64:67], v199 offset:24576
	ds_read_b128 v[68:71], v199 offset:25600
	s_waitcnt lgkmcnt(1)
	v_mfma_f32_16x16x32_bf16 v[64:67], v[44:47], v[64:67], 0
	s_waitcnt lgkmcnt(0)
	v_mfma_f32_16x16x32_bf16 v[64:67], v[48:51], v[68:71], v[64:67]
	ds_read_b128 v[68:71], v199 offset:26624
	ds_read_b128 v[236:239], v199 offset:27648
	s_waitcnt lgkmcnt(1)
	v_mfma_f32_16x16x32_bf16 v[64:67], v[52:55], v[68:71], v[64:67]
	ds_read_b128 v[68:71], v199 offset:28672
	s_waitcnt lgkmcnt(1)
	v_mfma_f32_16x16x32_bf16 v[64:67], v[60:63], v[236:239], v[64:67]
	ds_read_b128 v[236:239], v199 offset:29696
	s_waitcnt lgkmcnt(1)
	v_mfma_f32_16x16x32_bf16 v[68:71], v[44:47], v[68:71], 0
	s_waitcnt lgkmcnt(0)
	v_mfma_f32_16x16x32_bf16 v[68:71], v[48:51], v[236:239], v[68:71]
	ds_read_b128 v[236:239], v199 offset:30720
	s_waitcnt lgkmcnt(0)
	v_mfma_f32_16x16x32_bf16 v[68:71], v[52:55], v[236:239], v[68:71]
	ds_read_b128 v[236:239], v199 offset:31744
	s_waitcnt lgkmcnt(0)
	v_mfma_f32_16x16x32_bf16 v[68:71], v[60:63], v[236:239], v[68:71]
	s_add_i32 s45, s45, s34
	s_cmpk_gt_i32 s45, 0x3ff
	s_cselect_b64 s[16:17], -1, 0
	s_and_b64 vcc, exec, s[16:17]
	s_cbranch_vccnz .LBB0_902
	s_bfe_u32 s98, s45, 0x20005
	s_lshl_b32 s98, s98, 2
	v_mov_b32_e32 v241, s98
	global_load_dword v242, v241, s[54:55]
	global_load_dword v243, v241, s[54:55] offset:16
	s_ashr_i32 s48, s45, 7
	s_and_b32 s64, s45, 31
	s_ashr_i32 s49, s48, 31
	s_lshl_b64 s[52:53], s[48:49], 12
	s_lshl_b32 s4, s64, 7
	s_or_b32 s52, s52, s4
	s_mul_i32 s4, s53, 0x1c00
	s_mul_hi_u32 s49, s52, 0x1c00
	s_bfe_u32 s47, s45, 0x20005
	s_add_i32 s49, s49, s4
	s_mul_i32 s4, s52, 0x1c00
	s_add_u32 s62, s0, s4
	s_addc_u32 s49, s1, s49
	s_lshl_b32 s4, s47, 8
	s_add_u32 s62, s62, s4
	s_addc_u32 s63, s49, 0
	s_lshl_b32 s48, s48, 2
	s_ashr_i32 s49, s48, 31
	s_or_b32 s48, s48, s47
	s_lshl_b64 s[48:49], s[48:49], 20
	s_add_u32 s47, s11, s48
	s_addc_u32 s49, s13, s49
	s_lshl_b32 s48, s64, 15
	s_add_u32 s48, s47, s48
	s_addc_u32 s49, s49, 0
	v_mov_b32_e32 v199, v167
	v_lshl_add_u64 v[40:41], s[48:49], 0, v[198:199]
	v_add_co_u32_e32 v16, vcc, s28, v40
	v_lshl_add_u64 v[42:43], s[52:53], 0, v[170:171]
	s_nop 0
	v_addc_co_u32_e32 v17, vcc, 0, v41, vcc
	v_mov_b64_e32 v[44:45], s[0:1]
	v_add_co_u32_e32 v28, vcc, s30, v40
	v_mad_u64_u32 v[44:45], s[52:53], v42, s26, v[44:45]
	v_lshl_add_u64 v[8:9], s[62:63], 0, v[166:167]
	v_addc_co_u32_e32 v29, vcc, 0, v41, vcc
	v_mad_i32_i24 v45, v43, s26, v45
	v_lshl_add_u64 v[32:33], v[8:9], 0, v[196:197]
	v_add_co_u32_e32 v40, vcc, s31, v40
	v_lshl_add_u64 v[42:43], v[44:45], 0, s[4:5]
	v_mov_b32_e32 v201, v167
	v_lshl_add_u64 v[4:5], v[8:9], 0, v[194:195]
	v_lshl_add_u64 v[24:25], v[32:33], 0, s[6:7]
	v_lshl_add_u64 v[36:37], v[32:33], 0, s[8:9]
	v_addc_co_u32_e32 v41, vcc, 0, v41, vcc
	v_lshl_add_u64 v[60:61], v[42:43], 0, v[200:201]
	global_load_dwordx4 v[0:3], v[4:5], off offset:1024
	s_nop 0
	global_load_dwordx4 v[4:7], v[4:5], off offset:2048
	s_nop 0
	global_load_dwordx4 v[8:11], v[32:33], off offset:1024
	global_load_dwordx4 v[12:15], v[32:33], off offset:2048
	s_nop 0
	global_load_dwordx4 v[16:19], v[16:17], off
	s_nop 0
	global_load_dwordx4 v[20:23], v[24:25], off offset:1024
	s_nop 0
	global_load_dwordx4 v[24:27], v[24:25], off offset:2048
	s_nop 0
	global_load_dwordx4 v[28:31], v[28:29], off
	s_nop 0
	global_load_dwordx4 v[32:35], v[36:37], off offset:1024
	s_nop 0
	global_load_dwordx4 v[36:39], v[36:37], off offset:2048
	s_nop 0
	global_load_dwordx4 v[40:43], v[40:41], off
	s_nop 0
	global_load_dwordx4 v[44:47], v[60:61], off
	global_load_dwordx4 v[48:51], v[60:61], off offset:64
	global_load_dwordx4 v[52:55], v[60:61], off offset:128
	global_load_dwordx4 v[56:59], v198, s[48:49]
	s_nop 0
	global_load_dwordx4 v[60:63], v[60:61], off offset:192
	s_branch .LBB0_902
